# gla_s3: 16 two-byte OG row stores per chunk widened to two dwordx4 stores through a per-wave LDS transposition (doc lever: pair narrow stores into wide ones); bf16 RNE via v_cvt_pk_bf16_f32
# baseline (speedup 1.0000x reference)
.LBB0_737:
	s_or_b64 exec, exec, s[10:11]
	s_lshr_b32 s4, s23, 2
	s_lshl_b32 s5, s22, 1
	s_and_b32 s10, s4, 3
	s_lshl_b32 s4, s18, 1
	s_and_b32 s5, s5, 0x300
	s_or_b32 s13, s5, s4
	s_lshl_b32 s4, s23, 7
	s_and_b32 s4, s4, 0x180
	s_or_b32 s5, s4, s18
	s_lshl_b32 s4, s14, 3
	s_lshl_b32 s14, s14, 2
	s_or_b32 s14, s14, s15
	s_ashr_i32 s15, s14, 31
	s_lshl_b32 s11, s10, 10
	s_lshl_b64 s[16:17], s[14:15], 8
	s_add_u32 s15, s16, s19
	s_addc_u32 s14, s17, s20
	s_lshl_b32 s38, s5, 2
	v_mov_b32_e32 v1, s14
	v_or_b32_e32 v0, s15, v176
	v_mov_b32_e32 v3, s14
	v_or_b32_e32 v2, s15, v180
	v_lshl_add_u64 v[64:65], v[178:179], 0, s[38:39]
	v_lshlrev_b64 v[0:1], 11, v[0:1]
	v_lshlrev_b64 v[2:3], 11, v[2:3]
	v_lshl_add_u64 v[0:1], v[64:65], 0, v[0:1]
	v_lshl_add_u64 v[2:3], v[64:65], 0, v[2:3]
	global_load_dword v0, v[0:1], off
	v_mov_b32_e32 v5, s14
	global_load_dword v1, v[2:3], off
	v_mov_b32_e32 v3, s14
	v_or_b32_e32 v2, s15, v182
	v_or_b32_e32 v4, s15, v184
	v_lshlrev_b64 v[2:3], 11, v[2:3]
	v_lshlrev_b64 v[4:5], 11, v[4:5]
	v_lshl_add_u64 v[2:3], v[64:65], 0, v[2:3]
	v_lshl_add_u64 v[4:5], v[64:65], 0, v[4:5]
	global_load_dword v2, v[2:3], off
	v_mov_b32_e32 v7, s14
	global_load_dword v3, v[4:5], off
	v_mov_b32_e32 v5, s14
	v_or_b32_e32 v4, s15, v186
	v_or_b32_e32 v6, s15, v188
	v_lshlrev_b64 v[4:5], 11, v[4:5]
	v_lshlrev_b64 v[6:7], 11, v[6:7]
	v_lshl_add_u64 v[4:5], v[64:65], 0, v[4:5]
	v_lshl_add_u64 v[6:7], v[64:65], 0, v[6:7]
	global_load_dword v4, v[4:5], off
	v_mov_b32_e32 v9, s14
	global_load_dword v5, v[6:7], off
	v_mov_b32_e32 v7, s14
	v_or_b32_e32 v6, s15, v190
	v_or_b32_e32 v8, s15, v192
	v_lshlrev_b64 v[6:7], 11, v[6:7]
	v_lshlrev_b64 v[8:9], 11, v[8:9]
	v_lshl_add_u64 v[6:7], v[64:65], 0, v[6:7]
	v_lshl_add_u64 v[8:9], v[64:65], 0, v[8:9]
	global_load_dword v6, v[6:7], off
	v_mov_b32_e32 v11, s14
	global_load_dword v7, v[8:9], off
	v_mov_b32_e32 v9, s14
	v_or_b32_e32 v8, s15, v194
	v_or_b32_e32 v10, s15, v196
	v_lshlrev_b64 v[8:9], 11, v[8:9]
	v_lshlrev_b64 v[10:11], 11, v[10:11]
	v_lshl_add_u64 v[8:9], v[64:65], 0, v[8:9]
	v_lshl_add_u64 v[10:11], v[64:65], 0, v[10:11]
	global_load_dword v8, v[8:9], off
	v_mov_b32_e32 v13, s14
	global_load_dword v9, v[10:11], off
	v_mov_b32_e32 v11, s14
	v_or_b32_e32 v10, s15, v198
	v_or_b32_e32 v12, s15, v200
	v_lshlrev_b64 v[10:11], 11, v[10:11]
	v_lshlrev_b64 v[12:13], 11, v[12:13]
	v_lshl_add_u64 v[10:11], v[64:65], 0, v[10:11]
	v_lshl_add_u64 v[12:13], v[64:65], 0, v[12:13]
	global_load_dword v10, v[10:11], off
	v_mov_b32_e32 v15, s14
	global_load_dword v11, v[12:13], off
	v_mov_b32_e32 v13, s14
	v_or_b32_e32 v12, s15, v202
	v_or_b32_e32 v14, s15, v204
	v_lshlrev_b64 v[12:13], 11, v[12:13]
	v_lshlrev_b64 v[14:15], 11, v[14:15]
	v_lshl_add_u64 v[12:13], v[64:65], 0, v[12:13]
	v_lshl_add_u64 v[14:15], v[64:65], 0, v[14:15]
	global_load_dword v12, v[12:13], off
	v_mov_b32_e32 v17, s14
	global_load_dword v13, v[14:15], off
	v_mov_b32_e32 v15, s14
	v_or_b32_e32 v14, s15, v206
	v_or_b32_e32 v16, s15, v208
	v_lshlrev_b64 v[14:15], 11, v[14:15]
	v_lshlrev_b64 v[16:17], 11, v[16:17]
	v_lshl_add_u64 v[14:15], v[64:65], 0, v[14:15]
	v_lshl_add_u64 v[16:17], v[64:65], 0, v[16:17]
	s_or_b32 s16, s15, 32
	global_load_dword v14, v[14:15], off
	v_mov_b32_e32 v19, s14
	global_load_dword v15, v[16:17], off
	v_mov_b32_e32 v17, s14
	v_or_b32_e32 v16, s16, v176
	v_or_b32_e32 v18, s16, v180
	v_lshlrev_b64 v[16:17], 11, v[16:17]
	v_lshlrev_b64 v[18:19], 11, v[18:19]
	v_lshl_add_u64 v[16:17], v[64:65], 0, v[16:17]
	v_lshl_add_u64 v[18:19], v[64:65], 0, v[18:19]
	global_load_dword v16, v[16:17], off
	v_mov_b32_e32 v21, s14
	global_load_dword v17, v[18:19], off
	v_mov_b32_e32 v19, s14
	v_or_b32_e32 v18, s16, v182
	v_or_b32_e32 v20, s16, v184
	v_lshlrev_b64 v[18:19], 11, v[18:19]
	v_lshlrev_b64 v[20:21], 11, v[20:21]
	v_lshl_add_u64 v[18:19], v[64:65], 0, v[18:19]
	v_lshl_add_u64 v[20:21], v[64:65], 0, v[20:21]
	global_load_dword v18, v[18:19], off
	v_mov_b32_e32 v23, s14
	global_load_dword v19, v[20:21], off
	v_mov_b32_e32 v21, s14
	v_or_b32_e32 v20, s16, v186
	v_or_b32_e32 v22, s16, v188
	v_lshlrev_b64 v[20:21], 11, v[20:21]
	v_lshlrev_b64 v[22:23], 11, v[22:23]
	v_lshl_add_u64 v[20:21], v[64:65], 0, v[20:21]
	v_lshl_add_u64 v[22:23], v[64:65], 0, v[22:23]
	global_load_dword v20, v[20:21], off
	v_mov_b32_e32 v25, s14
	global_load_dword v21, v[22:23], off
	v_mov_b32_e32 v23, s14
	v_or_b32_e32 v22, s16, v190
	v_or_b32_e32 v24, s16, v192
	v_lshlrev_b64 v[22:23], 11, v[22:23]
	v_lshlrev_b64 v[24:25], 11, v[24:25]
	v_lshl_add_u64 v[22:23], v[64:65], 0, v[22:23]
	v_lshl_add_u64 v[24:25], v[64:65], 0, v[24:25]
	global_load_dword v22, v[22:23], off
	v_mov_b32_e32 v27, s14
	global_load_dword v23, v[24:25], off
	v_mov_b32_e32 v25, s14
	v_or_b32_e32 v24, s16, v194
	v_or_b32_e32 v26, s16, v196
	v_lshlrev_b64 v[24:25], 11, v[24:25]
	v_lshlrev_b64 v[26:27], 11, v[26:27]
	v_lshl_add_u64 v[24:25], v[64:65], 0, v[24:25]
	v_lshl_add_u64 v[26:27], v[64:65], 0, v[26:27]
	global_load_dword v24, v[24:25], off
	v_mov_b32_e32 v29, s14
	global_load_dword v25, v[26:27], off
	v_mov_b32_e32 v27, s14
	v_or_b32_e32 v26, s16, v198
	v_or_b32_e32 v28, s16, v200
	v_lshlrev_b64 v[26:27], 11, v[26:27]
	v_lshlrev_b64 v[28:29], 11, v[28:29]
	v_lshl_add_u64 v[26:27], v[64:65], 0, v[26:27]
	v_lshl_add_u64 v[28:29], v[64:65], 0, v[28:29]
	global_load_dword v26, v[26:27], off
	v_mov_b32_e32 v31, s14
	global_load_dword v27, v[28:29], off
	v_mov_b32_e32 v29, s14
	v_or_b32_e32 v28, s16, v202
	v_or_b32_e32 v30, s16, v204
	v_lshlrev_b64 v[28:29], 11, v[28:29]
	v_lshlrev_b64 v[30:31], 11, v[30:31]
	v_lshl_add_u64 v[28:29], v[64:65], 0, v[28:29]
	v_lshl_add_u64 v[30:31], v[64:65], 0, v[30:31]
	global_load_dword v28, v[28:29], off
	v_mov_b32_e32 v33, s14
	global_load_dword v29, v[30:31], off
	v_mov_b32_e32 v31, s14
	v_or_b32_e32 v30, s16, v206
	v_or_b32_e32 v32, s16, v208
	v_lshlrev_b64 v[30:31], 11, v[30:31]
	v_lshlrev_b64 v[32:33], 11, v[32:33]
	v_lshl_add_u64 v[30:31], v[64:65], 0, v[30:31]
	v_lshl_add_u64 v[32:33], v[64:65], 0, v[32:33]
	s_or_b32 s16, s15, 64
	global_load_dword v30, v[30:31], off
	v_mov_b32_e32 v35, s14
	global_load_dword v31, v[32:33], off
	v_mov_b32_e32 v33, s14
	v_or_b32_e32 v32, s16, v176
	v_or_b32_e32 v34, s16, v180
	v_lshlrev_b64 v[32:33], 11, v[32:33]
	v_lshlrev_b64 v[34:35], 11, v[34:35]
	v_lshl_add_u64 v[32:33], v[64:65], 0, v[32:33]
	v_lshl_add_u64 v[34:35], v[64:65], 0, v[34:35]
	global_load_dword v32, v[32:33], off
	v_mov_b32_e32 v37, s14
	global_load_dword v33, v[34:35], off
	v_mov_b32_e32 v35, s14
	v_or_b32_e32 v34, s16, v182
	v_or_b32_e32 v36, s16, v184
	v_lshlrev_b64 v[34:35], 11, v[34:35]
	v_lshlrev_b64 v[36:37], 11, v[36:37]
	v_lshl_add_u64 v[34:35], v[64:65], 0, v[34:35]
	v_lshl_add_u64 v[36:37], v[64:65], 0, v[36:37]
	global_load_dword v34, v[34:35], off
	v_mov_b32_e32 v39, s14
	global_load_dword v35, v[36:37], off
	v_mov_b32_e32 v37, s14
	v_or_b32_e32 v36, s16, v186
	v_or_b32_e32 v38, s16, v188
	v_lshlrev_b64 v[36:37], 11, v[36:37]
	v_lshlrev_b64 v[38:39], 11, v[38:39]
	v_lshl_add_u64 v[36:37], v[64:65], 0, v[36:37]
	v_lshl_add_u64 v[38:39], v[64:65], 0, v[38:39]
	global_load_dword v36, v[36:37], off
	v_mov_b32_e32 v41, s14
	global_load_dword v37, v[38:39], off
	v_mov_b32_e32 v39, s14
	v_or_b32_e32 v38, s16, v190
	v_or_b32_e32 v40, s16, v192
	v_lshlrev_b64 v[38:39], 11, v[38:39]
	v_lshlrev_b64 v[40:41], 11, v[40:41]
	v_lshl_add_u64 v[38:39], v[64:65], 0, v[38:39]
	v_lshl_add_u64 v[40:41], v[64:65], 0, v[40:41]
	global_load_dword v38, v[38:39], off
	v_mov_b32_e32 v43, s14
	global_load_dword v39, v[40:41], off
	v_mov_b32_e32 v41, s14
	v_or_b32_e32 v40, s16, v194
	v_or_b32_e32 v42, s16, v196
	v_lshlrev_b64 v[40:41], 11, v[40:41]
	v_lshlrev_b64 v[42:43], 11, v[42:43]
	v_lshl_add_u64 v[40:41], v[64:65], 0, v[40:41]
	v_lshl_add_u64 v[42:43], v[64:65], 0, v[42:43]
	global_load_dword v40, v[40:41], off
	v_mov_b32_e32 v45, s14
	global_load_dword v41, v[42:43], off
	v_mov_b32_e32 v43, s14
	v_or_b32_e32 v42, s16, v198
	v_or_b32_e32 v44, s16, v200
	v_lshlrev_b64 v[42:43], 11, v[42:43]
	v_lshlrev_b64 v[44:45], 11, v[44:45]
	v_lshl_add_u64 v[42:43], v[64:65], 0, v[42:43]
	v_lshl_add_u64 v[44:45], v[64:65], 0, v[44:45]
	global_load_dword v42, v[42:43], off
	v_mov_b32_e32 v47, s14
	global_load_dword v43, v[44:45], off
	v_mov_b32_e32 v45, s14
	v_or_b32_e32 v44, s16, v202
	v_or_b32_e32 v46, s16, v204
	v_lshlrev_b64 v[44:45], 11, v[44:45]
	v_lshlrev_b64 v[46:47], 11, v[46:47]
	v_lshl_add_u64 v[44:45], v[64:65], 0, v[44:45]
	v_lshl_add_u64 v[46:47], v[64:65], 0, v[46:47]
	global_load_dword v44, v[44:45], off
	v_mov_b32_e32 v49, s14
	global_load_dword v45, v[46:47], off
	v_mov_b32_e32 v47, s14
	v_or_b32_e32 v46, s16, v206
	v_or_b32_e32 v48, s16, v208
	v_lshlrev_b64 v[46:47], 11, v[46:47]
	v_lshlrev_b64 v[48:49], 11, v[48:49]
	v_lshl_add_u64 v[46:47], v[64:65], 0, v[46:47]
	v_lshl_add_u64 v[48:49], v[64:65], 0, v[48:49]
	s_or_b32 s15, s15, 0x60
	global_load_dword v46, v[46:47], off
	v_mov_b32_e32 v51, s14
	global_load_dword v47, v[48:49], off
	v_mov_b32_e32 v49, s14
	v_or_b32_e32 v48, s15, v176
	v_or_b32_e32 v50, s15, v180
	v_lshlrev_b64 v[48:49], 11, v[48:49]
	v_lshlrev_b64 v[50:51], 11, v[50:51]
	v_lshl_add_u64 v[48:49], v[64:65], 0, v[48:49]
	v_lshl_add_u64 v[50:51], v[64:65], 0, v[50:51]
	global_load_dword v48, v[48:49], off
	v_mov_b32_e32 v53, s14
	global_load_dword v49, v[50:51], off
	v_mov_b32_e32 v51, s14
	v_or_b32_e32 v50, s15, v182
	v_or_b32_e32 v52, s15, v184
	v_lshlrev_b64 v[50:51], 11, v[50:51]
	v_lshlrev_b64 v[52:53], 11, v[52:53]
	v_lshl_add_u64 v[50:51], v[64:65], 0, v[50:51]
	v_lshl_add_u64 v[52:53], v[64:65], 0, v[52:53]
	global_load_dword v50, v[50:51], off
	v_mov_b32_e32 v55, s14
	global_load_dword v51, v[52:53], off
	v_mov_b32_e32 v53, s14
	v_or_b32_e32 v52, s15, v186
	v_or_b32_e32 v54, s15, v188
	v_lshlrev_b64 v[52:53], 11, v[52:53]
	v_lshlrev_b64 v[54:55], 11, v[54:55]
	v_lshl_add_u64 v[52:53], v[64:65], 0, v[52:53]
	v_lshl_add_u64 v[54:55], v[64:65], 0, v[54:55]
	global_load_dword v52, v[52:53], off
	v_mov_b32_e32 v57, s14
	global_load_dword v53, v[54:55], off
	v_mov_b32_e32 v55, s14
	v_or_b32_e32 v54, s15, v190
	v_or_b32_e32 v56, s15, v192
	v_lshlrev_b64 v[54:55], 11, v[54:55]
	v_lshlrev_b64 v[56:57], 11, v[56:57]
	v_lshl_add_u64 v[54:55], v[64:65], 0, v[54:55]
	v_lshl_add_u64 v[56:57], v[64:65], 0, v[56:57]
	global_load_dword v54, v[54:55], off
	v_mov_b32_e32 v59, s14
	global_load_dword v55, v[56:57], off
	v_mov_b32_e32 v57, s14
	v_or_b32_e32 v56, s15, v194
	v_or_b32_e32 v58, s15, v196
	v_lshlrev_b64 v[56:57], 11, v[56:57]
	v_lshlrev_b64 v[58:59], 11, v[58:59]
	v_lshl_add_u64 v[56:57], v[64:65], 0, v[56:57]
	v_lshl_add_u64 v[58:59], v[64:65], 0, v[58:59]
	global_load_dword v56, v[56:57], off
	v_mov_b32_e32 v61, s14
	global_load_dword v57, v[58:59], off
	v_mov_b32_e32 v59, s14
	v_or_b32_e32 v58, s15, v198
	v_or_b32_e32 v60, s15, v200
	v_lshlrev_b64 v[58:59], 11, v[58:59]
	v_lshlrev_b64 v[60:61], 11, v[60:61]
	v_lshl_add_u64 v[58:59], v[64:65], 0, v[58:59]
	v_lshl_add_u64 v[60:61], v[64:65], 0, v[60:61]
	global_load_dword v58, v[58:59], off
	v_mov_b32_e32 v63, s14
	global_load_dword v59, v[60:61], off
	v_mov_b32_e32 v61, s14
	v_or_b32_e32 v60, s15, v202
	v_or_b32_e32 v62, s15, v204
	v_lshlrev_b64 v[60:61], 11, v[60:61]
	v_lshlrev_b64 v[62:63], 11, v[62:63]
	v_lshl_add_u64 v[60:61], v[64:65], 0, v[60:61]
	v_lshl_add_u64 v[62:63], v[64:65], 0, v[62:63]
	global_load_dword v60, v[60:61], off
	v_mov_b32_e32 v67, s14
	global_load_dword v61, v[62:63], off
	v_mov_b32_e32 v63, s14
	v_or_b32_e32 v62, s15, v206
	v_or_b32_e32 v66, s15, v208
	v_lshlrev_b64 v[62:63], 11, v[62:63]
	v_lshlrev_b64 v[66:67], 11, v[66:67]
	v_lshl_add_u64 v[62:63], v[64:65], 0, v[62:63]
	v_lshl_add_u64 v[64:65], v[64:65], 0, v[66:67]
	global_load_dword v62, v[62:63], off
	v_lshl_or_b32 v160, s5, 7, v189
	global_load_dword v63, v[64:65], off
	s_ashr_i32 s5, s4, 31
	s_waitcnt vmcnt(0) lgkmcnt(0)
	ds_write_b128 v177, v[96:99]
	ds_write_b128 v177, v[104:107] offset:8192
	ds_write_b128 v177, v[112:115] offset:16384
	ds_write_b128 v177, v[120:123] offset:24576
	s_lshl_b64 s[4:5], s[4:5], 18
	s_waitcnt lgkmcnt(0)
	s_barrier
	s_or_b32 s4, s4, s11
	s_or_b32 s4, s4, s13
	v_lshl_add_u64 v[216:217], s[8:9], 0, v[160:161]
	v_lshl_add_u64 v[218:219], v[214:215], 0, s[4:5]
	v_and_b32_e32 v88, 63, v193
	v_lshrrev_b32_e32 v89, 5, v88
	v_and_b32_e32 v90, 31, v88
	v_lshlrev_b32_e32 v91, 14, v89
	v_lshl_add_u32 v91, v90, 1, v91
	v_lshrrev_b32_e32 v92, 2, v88
	v_and_b32_e32 v93, 3, v88
	v_lshlrev_b32_e32 v92, 12, v92
	v_lshl_add_u32 v92, v93, 4, v92
	v_sub_co_u32_e32 v242, vcc, v218, v91
	s_nop 1
	v_subbrev_co_u32_e32 v243, vcc, 0, v219, vcc
	v_add_co_u32_e32 v242, vcc, v242, v92
	s_nop 1
	v_addc_co_u32_e32 v243, vcc, 0, v243, vcc
	v_lshrrev_b32_e32 v94, 6, v193
	v_lshlrev_b32_e32 v94, 12, v94
	v_add_u32_e32 v94, 0x18000, v94
	v_mul_u32_u24_e32 v95, 0x140, v89
	v_lshl_add_u32 v95, v90, 1, v95
	v_add_u32_e32 v244, v94, v95
	v_lshrrev_b32_e32 v95, 2, v88
	v_mul_u32_u24_e32 v95, 0x50, v95
	v_lshl_add_u32 v95, v93, 4, v95
	v_add_u32_e32 v245, v94, v95
	s_add_i32 s10, s12, s10
	s_mov_b64 s[12:13], 0
	s_mov_b32 s24, 0
	s_branch .LBB0_739

.LBB0_741:
	s_and_b32 s11, s24, 0x8000
	v_add_u32_e32 v160, s11, v187
	v_cvt_pk_bf16_f32 v80, v0, v1
	v_cvt_pk_bf16_f32 v81, v2, v3
	v_cvt_pk_bf16_f32 v82, v4, v5
	v_cvt_pk_bf16_f32 v83, v6, v7
	ds_read_b128 v[64:67], v160
	ds_read_b128 v[84:87], v160 offset:16384
	s_waitcnt lgkmcnt(0)
	v_mfma_f32_32x32x16_bf16 v[64:79], v[64:67], v[80:83], 0
	v_cvt_pk_bf16_f32 v220, v8, v9
	v_cvt_pk_bf16_f32 v221, v10, v11
	v_cvt_pk_bf16_f32 v222, v12, v13
	v_cvt_pk_bf16_f32 v223, v14, v15
	ds_read_b128 v[224:227], v160 offset:1024
	ds_read_b128 v[228:231], v160 offset:17408
	v_mfma_f32_32x32x16_bf16 v[80:95], v[84:87], v[80:83], 0
	s_waitcnt lgkmcnt(0)
	v_mfma_f32_32x32x16_bf16 v[64:79], v[224:227], v[220:223], v[64:79]
	v_mfma_f32_32x32x16_bf16 v[80:95], v[228:231], v[220:223], v[80:95]
	v_cvt_pk_bf16_f32 v220, v16, v17
	v_cvt_pk_bf16_f32 v221, v18, v19
	v_cvt_pk_bf16_f32 v222, v20, v21
	v_cvt_pk_bf16_f32 v223, v22, v23
	ds_read_b128 v[224:227], v160 offset:2048
	ds_read_b128 v[228:231], v160 offset:18432
	s_waitcnt lgkmcnt(0)
	v_mfma_f32_32x32x16_bf16 v[64:79], v[224:227], v[220:223], v[64:79]
	v_mfma_f32_32x32x16_bf16 v[80:95], v[228:231], v[220:223], v[80:95]
	v_cvt_pk_bf16_f32 v220, v24, v25
	v_cvt_pk_bf16_f32 v221, v26, v27
	v_cvt_pk_bf16_f32 v222, v28, v29
	v_cvt_pk_bf16_f32 v223, v30, v31
	ds_read_b128 v[224:227], v160 offset:3072
	ds_read_b128 v[228:231], v160 offset:19456
	s_waitcnt lgkmcnt(0)
	v_mfma_f32_32x32x16_bf16 v[64:79], v[224:227], v[220:223], v[64:79]
	v_mfma_f32_32x32x16_bf16 v[80:95], v[228:231], v[220:223], v[80:95]
	v_cvt_pk_bf16_f32 v220, v32, v33
	v_cvt_pk_bf16_f32 v221, v34, v35
	v_cvt_pk_bf16_f32 v222, v36, v37
	v_cvt_pk_bf16_f32 v223, v38, v39
	ds_read_b128 v[224:227], v160 offset:4096
	ds_read_b128 v[228:231], v160 offset:20480
	s_waitcnt lgkmcnt(0)
	v_mfma_f32_32x32x16_bf16 v[64:79], v[224:227], v[220:223], v[64:79]
	v_cvt_pk_bf16_f32 v224, v40, v41
	v_cvt_pk_bf16_f32 v225, v42, v43
	v_cvt_pk_bf16_f32 v226, v44, v45
	v_cvt_pk_bf16_f32 v227, v46, v47
	v_mfma_f32_32x32x16_bf16 v[80:95], v[228:231], v[220:223], v[80:95]
	ds_read_b128 v[220:223], v160 offset:5120
	ds_read_b128 v[228:231], v160 offset:21504
	s_waitcnt lgkmcnt(0)
	v_mfma_f32_32x32x16_bf16 v[64:79], v[220:223], v[224:227], v[64:79]
	v_cvt_pk_bf16_f32 v220, v48, v49
	v_cvt_pk_bf16_f32 v221, v50, v51
	v_cvt_pk_bf16_f32 v222, v52, v53
	v_cvt_pk_bf16_f32 v223, v54, v55
	v_mfma_f32_32x32x16_bf16 v[80:95], v[228:231], v[224:227], v[80:95]
	ds_read_b128 v[224:227], v160 offset:6144
	ds_read_b128 v[228:231], v160 offset:22528
	s_waitcnt lgkmcnt(0)
	v_mfma_f32_32x32x16_bf16 v[64:79], v[224:227], v[220:223], v[64:79]
	v_cvt_pk_bf16_f32 v224, v56, v57
	v_cvt_pk_bf16_f32 v225, v58, v59
	v_cvt_pk_bf16_f32 v226, v60, v61
	v_cvt_pk_bf16_f32 v227, v62, v63
	v_mfma_f32_32x32x16_bf16 v[80:95], v[228:231], v[220:223], v[80:95]
	ds_read_b128 v[220:223], v160 offset:7168
	ds_read_b128 v[228:231], v160 offset:23552
	s_waitcnt lgkmcnt(0)
	v_mfma_f32_32x32x16_bf16 v[64:79], v[220:223], v[224:227], v[64:79]
	v_mfma_f32_32x32x16_bf16 v[80:95], v[228:231], v[224:227], v[80:95]
	s_nop 11
	v_cndmask_b32_e64 v160, v64, v80, s[6:7]
	v_cndmask_b32_e64 v203, v65, v81, s[6:7]
	v_cndmask_b32_e64 v205, v66, v82, s[6:7]
	v_cndmask_b32_e64 v207, v67, v83, s[6:7]
	v_cndmask_b32_e64 v209, v68, v84, s[6:7]
	v_cndmask_b32_e64 v211, v69, v85, s[6:7]
	v_cndmask_b32_e64 v220, v70, v86, s[6:7]
	v_cndmask_b32_e64 v221, v71, v87, s[6:7]
	v_cndmask_b32_e64 v222, v72, v88, s[6:7]
	v_cndmask_b32_e64 v223, v73, v89, s[6:7]
	v_cndmask_b32_e64 v224, v74, v90, s[6:7]
	v_cndmask_b32_e64 v225, v75, v91, s[6:7]
	v_cndmask_b32_e64 v226, v76, v92, s[6:7]
	v_cndmask_b32_e64 v227, v77, v93, s[6:7]
	v_cndmask_b32_e64 v228, v78, v94, s[6:7]
	v_cndmask_b32_e64 v229, v79, v95, s[6:7]
	ds_write2st64_b32 v181, v160, v203 offset0:64 offset1:65
	ds_write2st64_b32 v181, v205, v207 offset0:66 offset1:67
	ds_write2st64_b32 v181, v209, v211 offset0:68 offset1:69
	ds_write2st64_b32 v181, v220, v221 offset0:70 offset1:71
	ds_write2st64_b32 v181, v222, v223 offset0:72 offset1:73
	ds_write2st64_b32 v181, v224, v225 offset0:74 offset1:75
	ds_write2st64_b32 v181, v226, v227 offset0:76 offset1:77
	ds_write2st64_b32 v181, v228, v229 offset0:78 offset1:79
	s_waitcnt vmcnt(10)
	ds_write_b128 v183, v[100:103]
	ds_write_b128 v183, v[108:111] offset:8192
	ds_write_b128 v183, v[116:119] offset:16384
	ds_write_b128 v183, v[124:127] offset:24576
	s_and_saveexec_b64 s[4:5], s[0:1]
	ds_write_b32 v185, v201
	s_or_b64 exec, exec, s[4:5]
	s_waitcnt lgkmcnt(0)
	s_barrier
	ds_read2st64_b32 v[234:235], v191 offset1:1
	ds_read2st64_b32 v[232:233], v191 offset0:2 offset1:3
	ds_read2st64_b32 v[230:231], v191 offset0:4 offset1:5
	ds_read2st64_b32 v[228:229], v191 offset0:6 offset1:7
	ds_read2st64_b32 v[226:227], v191 offset0:8 offset1:9
	ds_read2st64_b32 v[224:225], v191 offset0:10 offset1:11
	ds_read2st64_b32 v[222:223], v191 offset0:12 offset1:13
	ds_read2st64_b32 v[220:221], v191 offset0:14 offset1:15
	v_cndmask_b32_e64 v160, 0, 1, s[14:15]
	v_cmp_ne_u32_e64 s[4:5], 1, v160
	s_andn2_b64 vcc, exec, s[14:15]
	s_cbranch_vccnz .Lmy_s3_last
	s_add_i32 s14, s10, 4
	s_ashr_i32 s15, s14, 31
	s_lshl_b64 s[16:17], s[14:15], 15
	v_lshl_add_u64 v[116:117], v[172:173], 0, s[16:17]
	v_add_co_u32_e32 v108, vcc, 0x2000, v116
	s_nop 1
	v_addc_co_u32_e32 v109, vcc, 0, v117, vcc
	v_add_co_u32_e32 v118, vcc, 0x4000, v116
	global_load_dwordx4 v[100:103], v[116:117], off
	s_nop 0
	global_load_dwordx4 v[108:111], v[108:109], off
	v_addc_co_u32_e32 v119, vcc, 0, v117, vcc
	v_add_co_u32_e32 v124, vcc, 0x6000, v116
	s_nop 1
	v_addc_co_u32_e32 v125, vcc, 0, v117, vcc
	global_load_dwordx4 v[116:119], v[118:119], off
	s_nop 0
	global_load_dwordx4 v[124:127], v[124:125], off
	s_and_saveexec_b64 s[16:17], s[0:1]
	s_cbranch_execz .LBB0_746
	s_lshl_b64 s[14:15], s[14:15], 10
	v_lshl_add_u64 v[240:241], v[174:175], 0, s[14:15]
	global_load_dword v201, v[240:241], off

.LBB0_747:
	v_cndmask_b32_e64 v64, v80, v64, s[6:7]
	v_cndmask_b32_e64 v65, v81, v65, s[6:7]
	v_cndmask_b32_e64 v66, v82, v66, s[6:7]
	v_cndmask_b32_e64 v67, v83, v67, s[6:7]
	v_cndmask_b32_e64 v68, v84, v68, s[6:7]
	v_cndmask_b32_e64 v69, v85, v69, s[6:7]
	v_cndmask_b32_e64 v70, v86, v70, s[6:7]
	v_cndmask_b32_e64 v71, v87, v71, s[6:7]
	v_cndmask_b32_e64 v72, v88, v72, s[6:7]
	v_cndmask_b32_e64 v73, v89, v73, s[6:7]
	v_cndmask_b32_e64 v74, v90, v74, s[6:7]
	v_cndmask_b32_e64 v75, v91, v75, s[6:7]
	v_cndmask_b32_e64 v76, v92, v76, s[6:7]
	v_cndmask_b32_e64 v77, v93, v77, s[6:7]
	v_cndmask_b32_e64 v78, v94, v78, s[6:7]
	v_cndmask_b32_e64 v79, v95, v79, s[6:7]
	s_waitcnt lgkmcnt(0)
	v_add_f32_e32 v64, v64, v234
	v_add_f32_e32 v65, v65, v235
	v_add_f32_e32 v66, v66, v232
	v_add_f32_e32 v67, v67, v233
	v_add_f32_e32 v68, v68, v230
	v_add_f32_e32 v69, v69, v231
	v_add_f32_e32 v70, v70, v228
	v_add_f32_e32 v71, v71, v229
	v_add_f32_e32 v72, v72, v226
	v_add_f32_e32 v73, v73, v227
	v_add_f32_e32 v74, v74, v224
	v_add_f32_e32 v75, v75, v225
	v_add_f32_e32 v76, v76, v222
	v_add_f32_e32 v77, v77, v223
	v_add_f32_e32 v78, v78, v220
	v_add_f32_e32 v79, v79, v221
	s_mov_b32 s14, 0x2ec00000
	v_add_u32_e32 v92, s21, v210
	s_waitcnt vmcnt(8)
	v_mfma_f32_32x32x16_bf16 v[64:79], v[144:147], v[140:143], v[64:79]
	v_mfma_f32_32x32x16_bf16 v[64:79], v[148:151], v[136:139], v[64:79]
	v_mfma_f32_32x32x16_bf16 v[64:79], v[152:155], v[132:135], v[64:79]
	v_mfma_f32_32x32x16_bf16 v[64:79], v[156:159], v[128:131], v[64:79]
	s_nop 11
	v_cvt_pk_bf16_f32 v80, v64, v65
	v_cvt_pk_bf16_f32 v81, v66, v67
	v_cvt_pk_bf16_f32 v82, v68, v69
	v_cvt_pk_bf16_f32 v83, v70, v71
	v_cvt_pk_bf16_f32 v84, v72, v73
	v_cvt_pk_bf16_f32 v85, v74, v75
	v_cvt_pk_bf16_f32 v86, v76, v77
	v_cvt_pk_bf16_f32 v87, v78, v79
	ds_write_b16 v244, v80
	ds_write_b16_d16_hi v244, v80 offset:80
	ds_write_b16 v244, v81 offset:160
	ds_write_b16_d16_hi v244, v81 offset:240
	ds_write_b16 v244, v82 offset:640
	ds_write_b16_d16_hi v244, v82 offset:720
	ds_write_b16 v244, v83 offset:800
	ds_write_b16_d16_hi v244, v83 offset:880
	ds_write_b16 v244, v84 offset:1280
	ds_write_b16_d16_hi v244, v84 offset:1360
	ds_write_b16 v244, v85 offset:1440
	ds_write_b16_d16_hi v244, v85 offset:1520
	ds_write_b16 v244, v86 offset:1920
	ds_write_b16_d16_hi v244, v86 offset:2000
	ds_write_b16 v244, v87 offset:2080
	ds_write_b16_d16_hi v244, v87 offset:2160
	v_lshl_add_u64 v[88:89], v[242:243], 0, s[12:13]
	s_mov_b32 s14, 0x2ec00000
	v_add_co_u32_e32 v88, vcc, s14, v88
	s_nop 1
	v_addc_co_u32_e32 v89, vcc, 0, v89, vcc
	ds_read_b128 v[64:67], v245
	ds_read_b128 v[68:71], v245 offset:1280
	v_add_co_u32_e32 v90, vcc, 0x10000, v88
	s_nop 1
	v_addc_co_u32_e32 v91, vcc, 0, v89, vcc
	s_waitcnt lgkmcnt(0)
	global_store_dwordx4 v[88:89], v[64:67], off
	global_store_dwordx4 v[90:91], v[68:71], off
	ds_read_b128 v[64:67], v92 offset:96
	ds_read_b128 v[68:71], v92 offset:64
	ds_read_b128 v[72:75], v92 offset:32
	ds_read_b128 v[76:79], v92
	s_and_b64 vcc, exec, s[4:5]
	s_waitcnt lgkmcnt(0)
	v_pk_mul_f32 v[12:13], v[12:13], v[64:65]
	v_pk_mul_f32 v[8:9], v[8:9], v[68:69]
	v_pk_mul_f32 v[14:15], v[14:15], v[66:67]
	v_pk_mul_f32 v[10:11], v[10:11], v[70:71]
	ds_read_b128 v[64:67], v92 offset:192
	ds_read_b128 v[68:71], v92 offset:224
	ds_read_b128 v[80:83], v92 offset:128
	ds_read_b128 v[84:87], v92 offset:160
	v_pk_mul_f32 v[4:5], v[4:5], v[72:73]
	v_pk_mul_f32 v[0:1], v[0:1], v[76:77]
	v_pk_mul_f32 v[6:7], v[6:7], v[74:75]
	v_pk_mul_f32 v[2:3], v[2:3], v[78:79]
	s_waitcnt lgkmcnt(0)
	v_pk_mul_f32 v[28:29], v[28:29], v[68:69]
	v_pk_mul_f32 v[24:25], v[24:25], v[64:65]
	v_pk_mul_f32 v[30:31], v[30:31], v[70:71]
	v_pk_mul_f32 v[26:27], v[26:27], v[66:67]
	ds_read_b128 v[64:67], v92 offset:320
	ds_read_b128 v[68:71], v92 offset:352
	ds_read_b128 v[72:75], v92 offset:256
	ds_read_b128 v[76:79], v92 offset:288
	ds_read_b128 v[88:91], v199
	v_pk_mul_f32 v[20:21], v[20:21], v[84:85]
	v_pk_mul_f32 v[16:17], v[16:17], v[80:81]
	v_pk_mul_f32 v[22:23], v[22:23], v[86:87]
	v_pk_mul_f32 v[18:19], v[18:19], v[82:83]
	ds_read_b128 v[80:83], v199 offset:4096
	ds_read_b128 v[84:87], v199 offset:1024
	s_waitcnt lgkmcnt(0)
	v_pk_mul_f32 v[44:45], v[44:45], v[68:69]
	v_pk_mul_f32 v[40:41], v[40:41], v[64:65]
	v_pk_mul_f32 v[36:37], v[36:37], v[76:77]
	v_pk_mul_f32 v[32:33], v[32:33], v[72:73]
	v_mfma_f32_32x32x16_bf16 v[0:15], v[88:91], v[140:143], v[0:15]
	v_mul_f32_e64 v46, v46, v70
	v_mul_f32_e64 v47, v47, v71
	v_mul_f32_e64 v42, v42, v66
	v_mul_f32_e64 v43, v43, v67
	v_mul_f32_e64 v38, v38, v78
	v_mul_f32_e64 v39, v39, v79
	ds_read_b128 v[64:67], v92 offset:448
	ds_read_b128 v[68:71], v92 offset:480
	ds_read_b128 v[76:79], v199 offset:8192
	ds_read_b128 v[88:91], v199 offset:5120
	v_pk_mul_f32 v[34:35], v[34:35], v[74:75]
	s_waitcnt lgkmcnt(0)
	v_pk_mul_f32 v[56:57], v[56:57], v[64:65]
	v_pk_mul_f32 v[60:61], v[60:61], v[68:69]
	v_mfma_f32_32x32x16_bf16 v[16:31], v[80:83], v[140:143], v[16:31]
	ds_read_b128 v[72:75], v92 offset:384
	ds_read_b128 v[80:83], v92 offset:416
	ds_read_b128 v[92:95], v199 offset:12288
	ds_read_b128 v[144:147], v199 offset:9216
	v_mul_f32_e64 v62, v62, v70
	v_mul_f32_e64 v63, v63, v71
	v_pk_mul_f32 v[58:59], v[58:59], v[66:67]
	s_waitcnt lgkmcnt(0)
	v_pk_mul_f32 v[48:49], v[48:49], v[72:73]
	v_pk_mul_f32 v[52:53], v[52:53], v[80:81]
	v_pk_mul_f32 v[54:55], v[54:55], v[82:83]
	v_pk_mul_f32 v[50:51], v[50:51], v[74:75]
	ds_read_b128 v[64:67], v199 offset:13312
	v_mfma_f32_32x32x16_bf16 v[32:47], v[76:79], v[140:143], v[32:47]
	v_mfma_f32_32x32x16_bf16 v[48:63], v[92:95], v[140:143], v[48:63]
	v_mfma_f32_32x32x16_bf16 v[0:15], v[84:87], v[136:139], v[0:15]
	v_mfma_f32_32x32x16_bf16 v[16:31], v[88:91], v[136:139], v[16:31]
	s_waitcnt lgkmcnt(0)
	v_mfma_f32_32x32x16_bf16 v[48:63], v[64:67], v[136:139], v[48:63]
	ds_read_b128 v[64:67], v199 offset:2048
	ds_read_b128 v[68:71], v199 offset:3072
	v_mfma_f32_32x32x16_bf16 v[32:47], v[144:147], v[136:139], v[32:47]
	s_waitcnt lgkmcnt(0)
	v_mfma_f32_32x32x16_bf16 v[0:15], v[64:67], v[132:135], v[0:15]
	ds_read_b128 v[64:67], v199 offset:6144
	ds_read_b128 v[72:75], v199 offset:7168
	s_waitcnt lgkmcnt(0)
	v_mfma_f32_32x32x16_bf16 v[16:31], v[64:67], v[132:135], v[16:31]
	ds_read_b128 v[64:67], v199 offset:10240
	ds_read_b128 v[76:79], v199 offset:11264
	s_waitcnt lgkmcnt(0)
	v_mfma_f32_32x32x16_bf16 v[32:47], v[64:67], v[132:135], v[32:47]
	ds_read_b128 v[64:67], v199 offset:14336
	ds_read_b128 v[80:83], v199 offset:15360
	s_waitcnt lgkmcnt(0)
	v_mfma_f32_32x32x16_bf16 v[48:63], v[64:67], v[132:135], v[48:63]
	v_mfma_f32_32x32x16_bf16 v[0:15], v[68:71], v[128:131], v[0:15]
	v_mfma_f32_32x32x16_bf16 v[16:31], v[72:75], v[128:131], v[16:31]
	v_mfma_f32_32x32x16_bf16 v[32:47], v[76:79], v[128:131], v[32:47]
	v_mfma_f32_32x32x16_bf16 v[48:63], v[80:83], v[128:131], v[48:63]
	s_cbranch_vccnz .LBB0_738
	s_xor_b32 s4, s11, 0x8000
	v_add_u32_e32 v64, s4, v177
	s_waitcnt vmcnt(6)
	ds_write_b128 v64, v[96:99]
	ds_write_b128 v64, v[104:107] offset:8192
	ds_write_b128 v64, v[112:115] offset:16384
	ds_write_b128 v64, v[120:123] offset:24576
	s_branch .LBB0_738
